# K2A1 + flat-release grid barrier: per-XCD generation words in one line polled by 16 lanes, no TOP counter round trip
# speedup vs baseline: 1.0674x; 1.0027x over previous
.LBB0_595:
	s_or_b64 exec, exec, s[4:5]
	v_cvt_f32_u32_e32 v4, v2
	s_waitcnt vmcnt(0)
	v_readfirstlane_b32 s4, v3
	v_sub_u32_e32 v3, 0, v2
	v_rcp_iflag_f32_e32 v4, v4
	v_add_u32_e32 v5, s4, v1
	v_mul_f32_e32 v4, 0x4f7ffffe, v4
	v_cvt_u32_f32_e32 v4, v4
	v_mul_lo_u32 v1, v3, v4
	v_mul_hi_u32 v1, v4, v1
	v_add_u32_e32 v1, v4, v1
	v_mul_hi_u32 v1, v5, v1
	v_mul_lo_u32 v3, v1, v2
	v_sub_u32_e32 v3, v5, v3
	v_add_u32_e32 v4, 1, v1
	v_cmp_ge_u32_e32 vcc, v3, v2
	s_nop 1
	v_cndmask_b32_e32 v1, v1, v4, vcc
	v_sub_u32_e32 v4, v3, v2
	v_cndmask_b32_e32 v3, v3, v4, vcc
	v_add_u32_e32 v4, 1, v1
	v_cmp_ge_u32_e32 vcc, v3, v2
	v_add_u32_e32 v3, 1, v5
	s_nop 0
	v_cndmask_b32_e32 v1, v1, v4, vcc
	v_mul_lo_u32 v4, v2, v1
	v_add_u32_e32 v2, v4, v2
	v_cmp_ne_u32_e32 vcc, v3, v2
	s_waitcnt lgkmcnt(0)
	s_cbranch_vccnz .Lgb_poll
	buffer_wbl2 sc1
	s_waitcnt vmcnt(0) lgkmcnt(0)
	v_readlane_b32 s6, v254, 40
	v_readlane_b32 s7, v254, 41
	v_readlane_b32 s8, v254, 36
	s_nop 3
	s_sub_u32 s8, s8, s6
	s_add_u32 s8, s8, 0x2000
	s_lshr_b32 s8, s8, 6
	s_add_u32 s6, s6, 0x400
	s_addc_u32 s7, s7, 0
	s_add_u32 s6, s6, s8
	s_addc_u32 s7, s7, 0
	v_mov_b32_e32 v2, 1
	s_nop 4
	global_atomic_add v81, v2, s[6:7]
.Lgb_poll:
	v_readlane_b32 s6, v254, 40
	v_readlane_b32 s7, v254, 41
	v_readfirstlane_b32 s9, v1
	v_readfirstlane_b32 s10, v0
	s_nop 3
	s_add_u32 s6, s6, 0x400
	s_addc_u32 s7, s7, 0
	s_mov_b64 s[14:15], exec
	s_mov_b32 exec_lo, 0xffff
	s_mov_b32 exec_hi, 0
	v_mbcnt_lo_u32_b32 v4, -1, 0
	v_lshlrev_b32_e32 v4, 2, v4
	s_mov_b32 s11, 0
.Lgb_spin:
	global_load_dword v5, v4, s[6:7] sc1
	s_waitcnt vmcnt(0)
	v_cmp_lt_u32_e32 vcc, s9, v5
	s_nop 1
	s_bcnt1_i32_b64 s16, vcc
	s_cmp_ge_u32 s16, s10
	s_cbranch_scc1 .Lgb_done
	s_sleep 1
	s_add_i32 s11, s11, 1
	s_and_b32 s16, s11, 0xff
	s_cmp_lg_u32 s16, 0
	s_cbranch_scc1 .Lgb_spin
	global_load_dword v6, v81, s[62:63] sc1
	s_waitcnt vmcnt(0)
	v_readfirstlane_b32 s16, v6
	s_nop 3
	s_cmp_lg_u32 s16, 0
	s_cbranch_scc1 .Lgb_done
	s_cmp_lt_u32 s11, 0x40001
	s_cbranch_scc1 .Lgb_spin
	s_mov_b64 exec, s[14:15]
	v_mov_b32_e32 v6, 1
	global_atomic_add v81, v6, s[62:63]
.Lgb_done:
	s_mov_b64 exec, s[14:15]
	s_waitcnt vmcnt(0)
	s_branch .LBB0_22
